# baseline (speedup 1.0000x reference)
; __device__ __forceinline__ float lo_bf(unsigned u) { return __uint_as_float(u << 16); }
; __device__ __forceinline__ float hi_bf(unsigned u) { return __uint_as_float(u & 0xffff0000u); }
; template <class Epi>
; __device__ __forceinline__ void gemm_tile(const u16* __restrict__ A, int lda, const u16* __restrict__ Wt, int K,
;                                           int m0, int n0, char* sbase, const Epi& epi) {
;     ...
;   if constexpr (Epi::kBatched) {
;     if (!epi.src_f32) {
; #pragma unroll
;       for (int ai = 0; ai < 2; ++ai) {
;         float4 gg[2][2];
;         uint2 rr[2][4][2];
; #pragma unroll
;         for (int bj = 0; bj < 2; ++bj)
; #pragma unroll
;           for (int n = 0; n < 2; ++n) gg[bj][n] = epi.loadG(m0, n0 + bj * 128 + wc * 32 + n * 16 + fq * 4);
; #pragma unroll
;         for (int bj = 0; bj < 2; ++bj)
; #pragma unroll
;           for (int m = 0; m < 4; ++m)
; #pragma unroll
;             for (int n = 0; n < 2; ++n)
;               rr[bj][m][n] = epi.loadR(m0 + ai * 128 + wr * 64 + m * 16 + fr, n0 + bj * 128 + wc * 32 + n * 16 + fq * 4);
; #pragma unroll
;         for (int bj = 0; bj < 2; ++bj)
; #pragma unroll
;           for (int m = 0; m < 4; ++m)
; #pragma unroll
;             for (int n = 0; n < 2; ++n)
;               epi.apply(m0 + ai * 128 + wr * 64 + m * 16 + fr, n0 + bj * 128 + wc * 32 + n * 16 + fq * 4, acc[ai][bj][m][n],
;                         rr[bj][m][n], gg[bj][n]);
;       }
;   __device__ __forceinline__ float4 loadG(int m, int n) const { return *(const float4*)(gate + (size_t)modrow(m) * 6144 + n); }
;   __device__ __forceinline__ void apply(int m, int n, f32x4 v, uint2 a, float4 g) const {
;     f32x4 o;
;     o[0] = lo_bf(a.x) + mul * g.x * v[0]; o[1] = hi_bf(a.x) + mul * g.y * v[1];
;     o[2] = lo_bf(a.y) + mul * g.z * v[2]; o[3] = hi_bf(a.y) + mul * g.w * v[3];
;     store4bf(p->Rb + (size_t)m * 1024 + n, o);
;   }
.LBB0_1814:
	s_or_b64 exec, exec, s[0:1]
	v_lshlrev_b32_e32 v0, 5, v146
	v_lshlrev_b32_e32 v132, 2, v147
	v_or3_b32 v0, v0, v132, s49
	v_or_b32_e32 v132, s48, v145
	v_add_u32_e32 v134, v132, v148
	v_or_b32_e32 v132, 48, v134
	v_ashrrev_i32_e32 v133, 31, v132
	v_lshlrev_b64 v[132:133], 11, v[132:133]
	v_ashrrev_i32_e32 v135, 31, v134
	s_min_i32 s0, s48, 0x10000
	v_lshl_add_u64 v[136:137], s[38:39], 0, v[132:133]
	v_lshlrev_b64 v[132:133], 11, v[134:135]
	v_or_b32_e32 v138, 16, v134
	v_or_b32_e32 v134, 32, v134
	s_lshr_b32 s0, s0, 11
	v_ashrrev_i32_e32 v139, 31, v138
	v_ashrrev_i32_e32 v135, 31, v134
	s_mulk_i32 s0, 0x6000
	v_lshlrev_b64 v[138:139], 11, v[138:139]
	v_lshlrev_b64 v[134:135], 11, v[134:135]
	s_add_u32 s12, s19, s0
	v_lshlrev_b32_e32 v160, 2, v0
	v_lshl_add_u64 v[132:133], s[38:39], 0, v[132:133]
	v_lshlrev_b32_e32 v0, 1, v0
	v_lshl_add_u64 v[138:139], s[38:39], 0, v[138:139]
	v_lshl_add_u64 v[134:135], s[38:39], 0, v[134:135]
	s_addc_u32 s13, s20, 0
	v_lshl_add_u64 v[132:133], v[132:133], 0, v[0:1]
	v_lshl_add_u64 v[146:147], v[138:139], 0, v[0:1]
	v_lshl_add_u64 v[140:141], v[134:135], 0, v[0:1]
	v_lshl_add_u64 v[136:137], v[136:137], 0, v[0:1]
	global_load_dwordx2 v[166:167], v[132:133], off
	global_load_dwordx2 v[168:169], v[132:133], off offset:32
	global_load_dwordx2 v[170:171], v[146:147], off
	global_load_dwordx2 v[172:173], v[146:147], off offset:32
	global_load_dwordx2 v[134:135], v[140:141], off
	global_load_dwordx2 v[174:175], v[140:141], off offset:32
	global_load_dwordx2 v[176:177], v[136:137], off
	global_load_dwordx2 v[158:159], v[136:137], off offset:32
	global_load_dwordx2 v[156:157], v[132:133], off offset:256
	global_load_dwordx2 v[154:155], v[132:133], off offset:288
	global_load_dwordx2 v[152:153], v[146:147], off offset:256
	global_load_dwordx2 v[150:151], v[146:147], off offset:288
	global_load_dwordx2 v[148:149], v[140:141], off offset:256
	global_load_dwordx2 v[144:145], v[140:141], off offset:288
	global_load_dwordx2 v[142:143], v[136:137], off offset:256
	global_load_dwordx2 v[138:139], v[136:137], off offset:288
	global_load_dwordx4 v[162:165], v160, s[12:13]
	global_load_dwordx4 v[208:211], v160, s[12:13]
	global_load_dwordx4 v[212:215], v160, s[12:13] offset:64
	global_load_dwordx4 v[216:219], v160, s[12:13] offset:512
	global_load_dwordx4 v[220:223], v160, s[12:13] offset:576
	v_mov_b32_e32 v186, 0x40000
	v_mov_b32_e32 v187, 0
	v_lshl_add_u64 v[186:187], v[132:133], 0, v[186:187]
	global_load_dwordx2 v[224:225], v[186:187], off
	global_load_dwordx2 v[226:227], v[186:187], off offset:32
	global_load_dwordx2 v[240:241], v[186:187], off offset:256
	global_load_dwordx2 v[242:243], v[186:187], off offset:288
	v_mov_b32_e32 v186, 0x48000
	v_mov_b32_e32 v187, 0
	v_lshl_add_u64 v[186:187], v[132:133], 0, v[186:187]
	global_load_dwordx2 v[228:229], v[186:187], off
	global_load_dwordx2 v[230:231], v[186:187], off offset:32
	global_load_dwordx2 v[244:245], v[186:187], off offset:256
	global_load_dwordx2 v[246:247], v[186:187], off offset:288
	v_mov_b32_e32 v186, 0x50000
	v_mov_b32_e32 v187, 0
	v_lshl_add_u64 v[186:187], v[132:133], 0, v[186:187]
	global_load_dwordx2 v[232:233], v[186:187], off
	global_load_dwordx2 v[234:235], v[186:187], off offset:32
	global_load_dwordx2 v[248:249], v[186:187], off offset:256
	global_load_dwordx2 v[250:251], v[186:187], off offset:288
	v_mov_b32_e32 v186, 0x58000
	v_mov_b32_e32 v187, 0
	v_lshl_add_u64 v[186:187], v[132:133], 0, v[186:187]
	global_load_dwordx2 v[236:237], v[186:187], off
	global_load_dwordx2 v[238:239], v[186:187], off offset:32
	global_load_dwordx2 v[182:183], v[186:187], off offset:256
	global_load_dwordx2 v[184:185], v[186:187], off offset:288
	s_mov_b64 s[0:1], 0x40000
	s_add_i32 s47, s47, s75
	s_add_i32 s46, s46, s44
	s_add_i32 s34, s34, s75
	s_cmp_ge_u32 s47, s21
	v_mov_b32_e32 v252, 0x358637bd
	s_waitcnt vmcnt(0)
	v_lshlrev_b32_e32 v178, 16, v166
	v_and_b32_e32 v179, 0xffff0000, v166
	v_pk_mul_f32 v[180:181], v[130:131], v[162:163]
	v_lshlrev_b32_e32 v162, 16, v167
	v_and_b32_e32 v163, 0xffff0000, v167
	v_pk_mul_f32 v[166:167], v[130:131], v[164:165]
	v_pk_fma_f32 v[126:127], v[126:127], v[180:181], v[178:179]
	v_pk_fma_f32 v[128:129], v[128:129], v[166:167], v[162:163]
	v_mov_b32_e32 v162, v212
	v_mov_b32_e32 v163, v213
	v_mov_b32_e32 v164, v214
	v_mov_b32_e32 v165, v215
	v_cvt_pk_bf16_f32 v126, v126, v127
	v_cvt_pk_bf16_f32 v127, v128, v129
	v_lshlrev_b32_e32 v128, 16, v168
	v_and_b32_e32 v129, 0xffff0000, v168
	v_pk_mul_f32 v[162:163], v[130:131], v[162:163]
	s_nop 0
	v_pk_fma_f32 v[122:123], v[122:123], v[162:163], v[128:129]
	v_lshlrev_b32_e32 v128, 16, v169
	v_and_b32_e32 v129, 0xffff0000, v169
	v_pk_mul_f32 v[164:165], v[130:131], v[164:165]
	v_cvt_pk_bf16_f32 v122, v122, v123
	v_pk_fma_f32 v[124:125], v[124:125], v[164:165], v[128:129]
	s_nop 0
	v_cvt_pk_bf16_f32 v123, v124, v125
	v_lshlrev_b32_e32 v124, 16, v170
	v_and_b32_e32 v125, 0xffff0000, v170
	v_pk_fma_f32 v[118:119], v[118:119], v[180:181], v[124:125]
	v_lshlrev_b32_e32 v124, 16, v171
	v_and_b32_e32 v125, 0xffff0000, v171
	v_pk_fma_f32 v[120:121], v[120:121], v[166:167], v[124:125]
	v_cvt_pk_bf16_f32 v118, v118, v119
	v_cvt_pk_bf16_f32 v119, v120, v121
	v_lshlrev_b32_e32 v120, 16, v172
	v_and_b32_e32 v121, 0xffff0000, v172
	v_pk_fma_f32 v[114:115], v[114:115], v[162:163], v[120:121]
	v_lshlrev_b32_e32 v120, 16, v173
	v_and_b32_e32 v121, 0xffff0000, v173
	v_pk_fma_f32 v[116:117], v[116:117], v[164:165], v[120:121]
	v_cvt_pk_bf16_f32 v114, v114, v115
	v_cvt_pk_bf16_f32 v115, v116, v117
	v_lshlrev_b32_e32 v116, 16, v134
	v_and_b32_e32 v117, 0xffff0000, v134
; __device__ __forceinline__ float lo_bf(unsigned u) { return __uint_as_float(u << 16); }
; __device__ __forceinline__ float hi_bf(unsigned u) { return __uint_as_float(u & 0xffff0000u); }
;   __device__ __forceinline__ float4 loadG(int m, int n) const { return *(const float4*)(gate + (size_t)modrow(m) * 6144 + n); }
; template <class Epi>
; __device__ __forceinline__ void gemm_tile(const u16* __restrict__ A, int lda, const u16* __restrict__ Wt, int K,
;                                           int m0, int n0, char* sbase, const Epi& epi) {
;     ...
;         for (int bj = 0; bj < 2; ++bj)
; #pragma unroll
;           for (int n = 0; n < 2; ++n) gg[bj][n] = epi.loadG(m0, n0 + bj * 128 + wc * 32 + n * 16 + fq * 4);
; #pragma unroll
;         for (int bj = 0; bj < 2; ++bj)
; #pragma unroll
;           for (int m = 0; m < 4; ++m)
; #pragma unroll
;             for (int n = 0; n < 2; ++n)
;               rr[bj][m][n] = epi.loadR(m0 + ai * 128 + wr * 64 + m * 16 + fr, n0 + bj * 128 + wc * 32 + n * 16 + fq * 4);
; #pragma unroll
;         for (int bj = 0; bj < 2; ++bj)
; #pragma unroll
;           for (int m = 0; m < 4; ++m)
; #pragma unroll
;             for (int n = 0; n < 2; ++n)
;               epi.apply(m0 + ai * 128 + wr * 64 + m * 16 + fr, n0 + bj * 128 + wc * 32 + n * 16 + fq * 4, acc[ai][bj][m][n],
;                         rr[bj][m][n], gg[bj][n]);
;       }
;   __device__ __forceinline__ void apply(int m, int n, f32x4 v, uint2 a, float4 g) const {
;     f32x4 o;
;     o[0] = lo_bf(a.x) + mul * g.x * v[0]; o[1] = hi_bf(a.x) + mul * g.y * v[1];
;     o[2] = lo_bf(a.y) + mul * g.z * v[2]; o[3] = hi_bf(a.y) + mul * g.w * v[3];
;     store4bf(p->Rb + (size_t)m * 1024 + n, o);
;   }
	v_pk_fma_f32 v[110:111], v[110:111], v[180:181], v[116:117]
	v_lshlrev_b32_e32 v116, 16, v135
	v_and_b32_e32 v117, 0xffff0000, v135
	v_pk_fma_f32 v[112:113], v[112:113], v[166:167], v[116:117]
	v_cvt_pk_bf16_f32 v110, v110, v111
	v_cvt_pk_bf16_f32 v111, v112, v113
	v_lshlrev_b32_e32 v112, 16, v174
	v_and_b32_e32 v113, 0xffff0000, v174
	v_pk_fma_f32 v[106:107], v[106:107], v[162:163], v[112:113]
	v_lshlrev_b32_e32 v112, 16, v175
	v_and_b32_e32 v113, 0xffff0000, v175
	v_pk_fma_f32 v[108:109], v[108:109], v[164:165], v[112:113]
	v_cvt_pk_bf16_f32 v106, v106, v107
	v_cvt_pk_bf16_f32 v107, v108, v109
	v_lshlrev_b32_e32 v108, 16, v176
	v_and_b32_e32 v109, 0xffff0000, v176
	v_pk_fma_f32 v[102:103], v[102:103], v[180:181], v[108:109]
	v_lshlrev_b32_e32 v108, 16, v177
	v_and_b32_e32 v109, 0xffff0000, v177
	v_pk_fma_f32 v[104:105], v[104:105], v[166:167], v[108:109]
	v_cvt_pk_bf16_f32 v102, v102, v103
	v_cvt_pk_bf16_f32 v103, v104, v105
	v_lshlrev_b32_e32 v104, 16, v158
	v_and_b32_e32 v105, 0xffff0000, v158
	v_pk_fma_f32 v[98:99], v[98:99], v[162:163], v[104:105]
	v_lshlrev_b32_e32 v104, 16, v159
	v_and_b32_e32 v105, 0xffff0000, v159
	v_pk_fma_f32 v[100:101], v[100:101], v[164:165], v[104:105]
	v_mov_b32_e32 v162, v216
	v_mov_b32_e32 v163, v217
	v_mov_b32_e32 v164, v218
	v_mov_b32_e32 v165, v219
	v_cvt_pk_bf16_f32 v98, v98, v99
	v_cvt_pk_bf16_f32 v99, v100, v101
	v_lshlrev_b32_e32 v100, 16, v156
	v_and_b32_e32 v101, 0xffff0000, v156
	v_lshlrev_b32_e32 v108, 16, v157
	v_and_b32_e32 v109, 0xffff0000, v157
	v_lshlrev_b32_e32 v112, 16, v154
	v_and_b32_e32 v113, 0xffff0000, v154
	v_pk_mul_f32 v[104:105], v[130:131], v[162:163]
	s_nop 0
	v_pk_fma_f32 v[94:95], v[94:95], v[104:105], v[100:101]
	v_pk_mul_f32 v[100:101], v[130:131], v[164:165]
	s_nop 0
	v_pk_fma_f32 v[96:97], v[96:97], v[100:101], v[108:109]
	v_cvt_pk_bf16_f32 v108, v94, v95
	v_cvt_pk_bf16_f32 v109, v96, v97
	v_mov_b32_e32 v94, v220
	v_mov_b32_e32 v95, v221
	v_mov_b32_e32 v96, v222
	v_mov_b32_e32 v97, v223
	s_nop 0
	global_store_dwordx2 v[132:133], v[126:127], off
	global_store_dwordx2 v[132:133], v[122:123], off offset:32
	global_store_dwordx2 v[146:147], v[118:119], off
	global_store_dwordx2 v[146:147], v[114:115], off offset:32
	global_store_dwordx2 v[140:141], v[110:111], off
	global_store_dwordx2 v[140:141], v[106:107], off offset:32
	global_store_dwordx2 v[136:137], v[102:103], off
	global_store_dwordx2 v[136:137], v[98:99], off offset:32
	global_store_dwordx2 v[132:133], v[108:109], off offset:256
	v_pk_mul_f32 v[94:95], v[130:131], v[94:95]
	s_nop 0
	v_pk_fma_f32 v[90:91], v[90:91], v[94:95], v[112:113]
	v_lshlrev_b32_e32 v112, 16, v155
	v_and_b32_e32 v113, 0xffff0000, v155
	v_pk_mul_f32 v[96:97], v[130:131], v[96:97]
	v_cvt_pk_bf16_f32 v90, v90, v91
	v_pk_fma_f32 v[92:93], v[92:93], v[96:97], v[112:113]
	s_nop 0
	v_cvt_pk_bf16_f32 v91, v92, v93
	global_store_dwordx2 v[132:133], v[90:91], off offset:288
	v_lshlrev_b32_e32 v90, 16, v152
	v_and_b32_e32 v91, 0xffff0000, v152
	v_pk_fma_f32 v[86:87], v[86:87], v[104:105], v[90:91]
	v_lshlrev_b32_e32 v90, 16, v153
	v_and_b32_e32 v91, 0xffff0000, v153
	v_pk_fma_f32 v[88:89], v[88:89], v[100:101], v[90:91]
	v_cvt_pk_bf16_f32 v86, v86, v87
	v_cvt_pk_bf16_f32 v87, v88, v89
	global_store_dwordx2 v[146:147], v[86:87], off offset:256
	v_lshlrev_b32_e32 v86, 16, v150
	v_and_b32_e32 v87, 0xffff0000, v150
	v_pk_fma_f32 v[82:83], v[82:83], v[94:95], v[86:87]
	v_lshlrev_b32_e32 v86, 16, v151
	v_and_b32_e32 v87, 0xffff0000, v151
	v_pk_fma_f32 v[84:85], v[84:85], v[96:97], v[86:87]
	v_cvt_pk_bf16_f32 v82, v82, v83
	v_cvt_pk_bf16_f32 v83, v84, v85
	global_store_dwordx2 v[146:147], v[82:83], off offset:288
	v_lshlrev_b32_e32 v82, 16, v148
	v_and_b32_e32 v83, 0xffff0000, v148
	v_pk_fma_f32 v[78:79], v[78:79], v[104:105], v[82:83]
	v_lshlrev_b32_e32 v82, 16, v149
	v_and_b32_e32 v83, 0xffff0000, v149
	v_pk_fma_f32 v[80:81], v[80:81], v[100:101], v[82:83]
	v_cvt_pk_bf16_f32 v78, v78, v79
	v_cvt_pk_bf16_f32 v79, v80, v81
	global_store_dwordx2 v[140:141], v[78:79], off offset:256
	v_lshlrev_b32_e32 v78, 16, v144
	v_and_b32_e32 v79, 0xffff0000, v144
	v_pk_fma_f32 v[74:75], v[74:75], v[94:95], v[78:79]
	v_lshlrev_b32_e32 v78, 16, v145
	v_and_b32_e32 v79, 0xffff0000, v145
	v_pk_fma_f32 v[76:77], v[76:77], v[96:97], v[78:79]
	v_cvt_pk_bf16_f32 v74, v74, v75
	v_cvt_pk_bf16_f32 v75, v76, v77
	global_store_dwordx2 v[140:141], v[74:75], off offset:288
	v_lshlrev_b32_e32 v74, 16, v142
	v_and_b32_e32 v75, 0xffff0000, v142
	v_pk_fma_f32 v[70:71], v[70:71], v[104:105], v[74:75]
	v_lshlrev_b32_e32 v74, 16, v143
	v_and_b32_e32 v75, 0xffff0000, v143
	v_pk_fma_f32 v[72:73], v[72:73], v[100:101], v[74:75]
	v_lshl_add_u64 v[78:79], v[132:133], 0, s[0:1]
	s_mov_b32 s0, 0x40000
	v_cvt_pk_bf16_f32 v70, v70, v71
	v_cvt_pk_bf16_f32 v71, v72, v73
	v_add_co_u32_e32 v86, vcc, s0, v132
	global_store_dwordx2 v[136:137], v[70:71], off offset:256
	v_lshlrev_b32_e32 v70, 16, v138
	v_and_b32_e32 v71, 0xffff0000, v138
	v_addc_co_u32_e32 v87, vcc, 0, v133, vcc
	s_mov_b32 s0, 0x48000
	v_pk_fma_f32 v[66:67], v[66:67], v[94:95], v[70:71]
	v_lshlrev_b32_e32 v70, 16, v139
	v_and_b32_e32 v71, 0xffff0000, v139
	v_add_co_u32_e32 v88, vcc, s0, v132
	s_mov_b64 s[0:1], 0x50000
	v_pk_fma_f32 v[68:69], v[68:69], v[96:97], v[70:71]
	v_addc_co_u32_e32 v89, vcc, 0, v133, vcc
	v_lshl_add_u64 v[70:71], v[132:133], 0, s[0:1]
	s_mov_b32 s0, 0x50000
	v_cvt_pk_bf16_f32 v66, v66, v67
	v_cvt_pk_bf16_f32 v67, v68, v69
	v_add_co_u32_e32 v90, vcc, s0, v132
	s_mov_b64 s[0:1], 0x58000
	global_store_dwordx2 v[136:137], v[66:67], off offset:288
	v_addc_co_u32_e32 v91, vcc, 0, v133, vcc
	v_lshl_add_u64 v[66:67], v[132:133], 0, s[0:1]
; __device__ __forceinline__ float lo_bf(unsigned u) { return __uint_as_float(u << 16); }
; __device__ __forceinline__ float hi_bf(unsigned u) { return __uint_as_float(u & 0xffff0000u); }
;   __device__ __forceinline__ float4 loadG(int m, int n) const { return *(const float4*)(gate + (size_t)modrow(m) * 6144 + n); }
; template <class Epi>
; __device__ __forceinline__ void gemm_tile(const u16* __restrict__ A, int lda, const u16* __restrict__ Wt, int K,
;                                           int m0, int n0, char* sbase, const Epi& epi) {
;     ...
;         for (int bj = 0; bj < 2; ++bj)
; #pragma unroll
;           for (int n = 0; n < 2; ++n) gg[bj][n] = epi.loadG(m0, n0 + bj * 128 + wc * 32 + n * 16 + fq * 4);
; #pragma unroll
;         for (int bj = 0; bj < 2; ++bj)
; #pragma unroll
;           for (int m = 0; m < 4; ++m)
; #pragma unroll
;             for (int n = 0; n < 2; ++n)
;               rr[bj][m][n] = epi.loadR(m0 + ai * 128 + wr * 64 + m * 16 + fr, n0 + bj * 128 + wc * 32 + n * 16 + fq * 4);
; #pragma unroll
;         for (int bj = 0; bj < 2; ++bj)
; #pragma unroll
;           for (int m = 0; m < 4; ++m)
; #pragma unroll
;             for (int n = 0; n < 2; ++n)
;               epi.apply(m0 + ai * 128 + wr * 64 + m * 16 + fr, n0 + bj * 128 + wc * 32 + n * 16 + fq * 4, acc[ai][bj][m][n],
;                         rr[bj][m][n], gg[bj][n]);
;       }
;   __device__ __forceinline__ void apply(int m, int n, f32x4 v, uint2 a, float4 g) const {
;     f32x4 o;
;     o[0] = lo_bf(a.x) + mul * g.x * v[0]; o[1] = hi_bf(a.x) + mul * g.y * v[1];
;     o[2] = lo_bf(a.y) + mul * g.z * v[2]; o[3] = hi_bf(a.y) + mul * g.w * v[3];
;     store4bf(p->Rb + (size_t)m * 1024 + n, o);
;   }
	s_mov_b32 s0, 0x58000
	v_add_co_u32_e32 v92, vcc, s0, v132
	v_mov_b32_e32 v102, v224
	v_mov_b32_e32 v103, v225
	v_mov_b32_e32 v104, v226
	v_mov_b32_e32 v105, v227
	v_addc_co_u32_e32 v93, vcc, 0, v133, vcc
	v_lshl_add_u64 v[74:75], v[132:133], 0, s[28:29]
	v_mov_b32_e32 v106, v228
	v_mov_b32_e32 v107, v229
	v_mov_b32_e32 v108, v230
	v_mov_b32_e32 v109, v231
	v_mov_b32_e32 v110, v232
	v_mov_b32_e32 v111, v233
	v_mov_b32_e32 v112, v234
	v_mov_b32_e32 v113, v235
	v_mov_b32_e32 v114, v236
	v_mov_b32_e32 v115, v237
	v_mov_b32_e32 v116, v238
	v_mov_b32_e32 v117, v239
	v_mov_b32_e32 v96, v240
	v_mov_b32_e32 v97, v241
	v_mov_b32_e32 v94, v242
	v_mov_b32_e32 v95, v243
	v_mov_b32_e32 v84, v244
	v_mov_b32_e32 v85, v245
	v_mov_b32_e32 v82, v246
	v_mov_b32_e32 v83, v247
	v_mov_b32_e32 v80, v248
	v_mov_b32_e32 v81, v249
	v_mov_b32_e32 v76, v250
	v_mov_b32_e32 v77, v251
	v_mov_b32_e32 v72, v182
	v_mov_b32_e32 v73, v183
	v_mov_b32_e32 v68, v184
	v_mov_b32_e32 v69, v185
	v_mov_b32_e32 v98, v208
	v_mov_b32_e32 v99, v209
	v_mov_b32_e32 v100, v210
	v_mov_b32_e32 v101, v211
	v_lshlrev_b32_e32 v118, 16, v102
	v_and_b32_e32 v119, 0xffff0000, v102
	v_pk_mul_f32 v[120:121], v[130:131], v[98:99]
	v_lshlrev_b32_e32 v98, 16, v103
	v_and_b32_e32 v99, 0xffff0000, v103
	v_pk_mul_f32 v[102:103], v[130:131], v[100:101]
	v_pk_fma_f32 v[62:63], v[62:63], v[120:121], v[118:119]
	v_pk_fma_f32 v[64:65], v[64:65], v[102:103], v[98:99]
	v_mov_b32_e32 v98, v212
	v_mov_b32_e32 v99, v213
	v_mov_b32_e32 v100, v214
	v_mov_b32_e32 v101, v215
	v_cvt_pk_bf16_f32 v62, v62, v63
	v_cvt_pk_bf16_f32 v63, v64, v65
	v_lshlrev_b32_e32 v64, 16, v104
	v_and_b32_e32 v65, 0xffff0000, v104
	v_pk_mul_f32 v[98:99], v[130:131], v[98:99]
	s_nop 0
	v_pk_fma_f32 v[58:59], v[58:59], v[98:99], v[64:65]
	v_lshlrev_b32_e32 v64, 16, v105
	v_and_b32_e32 v65, 0xffff0000, v105
	v_pk_mul_f32 v[100:101], v[130:131], v[100:101]
	v_cvt_pk_bf16_f32 v58, v58, v59
	v_pk_fma_f32 v[60:61], v[60:61], v[100:101], v[64:65]
	s_nop 0
	v_cvt_pk_bf16_f32 v59, v60, v61
	v_lshlrev_b32_e32 v60, 16, v106
	v_and_b32_e32 v61, 0xffff0000, v106
	v_pk_fma_f32 v[54:55], v[54:55], v[120:121], v[60:61]
	v_lshlrev_b32_e32 v60, 16, v107
	v_and_b32_e32 v61, 0xffff0000, v107
	v_pk_fma_f32 v[56:57], v[56:57], v[102:103], v[60:61]
	v_cvt_pk_bf16_f32 v54, v54, v55
	v_cvt_pk_bf16_f32 v55, v56, v57
	v_lshlrev_b32_e32 v56, 16, v108
	v_and_b32_e32 v57, 0xffff0000, v108
	v_pk_fma_f32 v[50:51], v[50:51], v[98:99], v[56:57]
	v_lshlrev_b32_e32 v56, 16, v109
	v_and_b32_e32 v57, 0xffff0000, v109
	v_pk_fma_f32 v[52:53], v[52:53], v[100:101], v[56:57]
	v_cvt_pk_bf16_f32 v50, v50, v51
	v_cvt_pk_bf16_f32 v51, v52, v53
	v_lshlrev_b32_e32 v52, 16, v110
	v_and_b32_e32 v53, 0xffff0000, v110
	v_pk_fma_f32 v[46:47], v[46:47], v[120:121], v[52:53]
	v_lshlrev_b32_e32 v52, 16, v111
	v_and_b32_e32 v53, 0xffff0000, v111
	v_pk_fma_f32 v[48:49], v[48:49], v[102:103], v[52:53]
	v_cvt_pk_bf16_f32 v46, v46, v47
	v_cvt_pk_bf16_f32 v47, v48, v49
	v_lshlrev_b32_e32 v48, 16, v112
	v_and_b32_e32 v49, 0xffff0000, v112
	v_pk_fma_f32 v[42:43], v[42:43], v[98:99], v[48:49]
	v_lshlrev_b32_e32 v48, 16, v113
	v_and_b32_e32 v49, 0xffff0000, v113
	v_pk_fma_f32 v[44:45], v[44:45], v[100:101], v[48:49]
	v_cvt_pk_bf16_f32 v42, v42, v43
	v_cvt_pk_bf16_f32 v43, v44, v45
	v_lshlrev_b32_e32 v44, 16, v114
	v_and_b32_e32 v45, 0xffff0000, v114
	v_pk_fma_f32 v[38:39], v[38:39], v[120:121], v[44:45]
	v_lshlrev_b32_e32 v44, 16, v115
	v_and_b32_e32 v45, 0xffff0000, v115
	v_pk_fma_f32 v[40:41], v[40:41], v[102:103], v[44:45]
	v_cvt_pk_bf16_f32 v38, v38, v39
	v_cvt_pk_bf16_f32 v39, v40, v41
	v_lshlrev_b32_e32 v40, 16, v116
	v_and_b32_e32 v41, 0xffff0000, v116
	v_pk_fma_f32 v[34:35], v[34:35], v[98:99], v[40:41]
	v_lshlrev_b32_e32 v40, 16, v117
	v_and_b32_e32 v41, 0xffff0000, v117
	v_pk_fma_f32 v[36:37], v[36:37], v[100:101], v[40:41]
; __device__ __forceinline__ float lo_bf(unsigned u) { return __uint_as_float(u << 16); }
; __device__ __forceinline__ float hi_bf(unsigned u) { return __uint_as_float(u & 0xffff0000u); }
;   __device__ __forceinline__ float4 loadG(int m, int n) const { return *(const float4*)(gate + (size_t)modrow(m) * 6144 + n); }
; template <class Epi>
; __device__ __forceinline__ void gemm_tile(const u16* __restrict__ A, int lda, const u16* __restrict__ Wt, int K,
;                                           int m0, int n0, char* sbase, const Epi& epi) {
;     ...
;         for (int bj = 0; bj < 2; ++bj)
; #pragma unroll
;           for (int n = 0; n < 2; ++n) gg[bj][n] = epi.loadG(m0, n0 + bj * 128 + wc * 32 + n * 16 + fq * 4);
; #pragma unroll
;         for (int bj = 0; bj < 2; ++bj)
; #pragma unroll
;           for (int m = 0; m < 4; ++m)
; #pragma unroll
;             for (int n = 0; n < 2; ++n)
;               rr[bj][m][n] = epi.loadR(m0 + ai * 128 + wr * 64 + m * 16 + fr, n0 + bj * 128 + wc * 32 + n * 16 + fq * 4);
; #pragma unroll
;         for (int bj = 0; bj < 2; ++bj)
; #pragma unroll
;           for (int m = 0; m < 4; ++m)
; #pragma unroll
;             for (int n = 0; n < 2; ++n)
;               epi.apply(m0 + ai * 128 + wr * 64 + m * 16 + fr, n0 + bj * 128 + wc * 32 + n * 16 + fq * 4, acc[ai][bj][m][n],
;                         rr[bj][m][n], gg[bj][n]);
;       }
;   __device__ __forceinline__ void apply(int m, int n, f32x4 v, uint2 a, float4 g) const {
;     f32x4 o;
;     o[0] = lo_bf(a.x) + mul * g.x * v[0]; o[1] = hi_bf(a.x) + mul * g.y * v[1];
;     o[2] = lo_bf(a.y) + mul * g.z * v[2]; o[3] = hi_bf(a.y) + mul * g.w * v[3];
;     store4bf(p->Rb + (size_t)m * 1024 + n, o);
;   }
	v_mov_b32_e32 v98, v216
	v_mov_b32_e32 v99, v217
	v_mov_b32_e32 v100, v218
	v_mov_b32_e32 v101, v219
	v_cvt_pk_bf16_f32 v34, v34, v35
	v_cvt_pk_bf16_f32 v35, v36, v37
	v_lshlrev_b32_e32 v36, 16, v96
	v_and_b32_e32 v37, 0xffff0000, v96
	v_lshlrev_b32_e32 v44, 16, v97
	v_and_b32_e32 v45, 0xffff0000, v97
	v_lshlrev_b32_e32 v48, 16, v94
	v_and_b32_e32 v49, 0xffff0000, v94
	v_pk_mul_f32 v[40:41], v[130:131], v[98:99]
	s_nop 0
	v_pk_fma_f32 v[30:31], v[30:31], v[40:41], v[36:37]
	v_pk_mul_f32 v[36:37], v[130:131], v[100:101]
	s_nop 0
	v_pk_fma_f32 v[32:33], v[32:33], v[36:37], v[44:45]
	v_cvt_pk_bf16_f32 v44, v30, v31
	v_cvt_pk_bf16_f32 v45, v32, v33
	v_mov_b32_e32 v30, v220
	v_mov_b32_e32 v31, v221
	v_mov_b32_e32 v32, v222
	v_mov_b32_e32 v33, v223
	s_nop 0
	global_store_dwordx2 v[86:87], v[62:63], off
	global_store_dwordx2 v[78:79], v[58:59], off offset:32
	global_store_dwordx2 v[88:89], v[54:55], off
	global_store_dwordx2 v[74:75], v[50:51], off offset:32
	global_store_dwordx2 v[90:91], v[46:47], off
	global_store_dwordx2 v[70:71], v[42:43], off offset:32
	global_store_dwordx2 v[92:93], v[38:39], off
	global_store_dwordx2 v[66:67], v[34:35], off offset:32
	global_store_dwordx2 v[78:79], v[44:45], off offset:256
	v_pk_mul_f32 v[30:31], v[130:131], v[30:31]
	s_nop 0
	v_pk_fma_f32 v[26:27], v[26:27], v[30:31], v[48:49]
	v_lshlrev_b32_e32 v48, 16, v95
	v_and_b32_e32 v49, 0xffff0000, v95
	v_pk_mul_f32 v[32:33], v[130:131], v[32:33]
	v_cvt_pk_bf16_f32 v26, v26, v27
	v_pk_fma_f32 v[28:29], v[28:29], v[32:33], v[48:49]
	s_nop 0
	v_cvt_pk_bf16_f32 v27, v28, v29
	global_store_dwordx2 v[78:79], v[26:27], off offset:288
	v_lshlrev_b32_e32 v26, 16, v84
	v_and_b32_e32 v27, 0xffff0000, v84
	v_pk_fma_f32 v[22:23], v[22:23], v[40:41], v[26:27]
	v_lshlrev_b32_e32 v26, 16, v85
	v_and_b32_e32 v27, 0xffff0000, v85
	v_pk_fma_f32 v[24:25], v[24:25], v[36:37], v[26:27]
	v_cvt_pk_bf16_f32 v22, v22, v23
	v_cvt_pk_bf16_f32 v23, v24, v25
	global_store_dwordx2 v[74:75], v[22:23], off offset:256
	v_lshlrev_b32_e32 v22, 16, v82
	v_and_b32_e32 v23, 0xffff0000, v82
	v_pk_fma_f32 v[18:19], v[18:19], v[30:31], v[22:23]
	v_lshlrev_b32_e32 v22, 16, v83
	v_and_b32_e32 v23, 0xffff0000, v83
	v_pk_fma_f32 v[20:21], v[20:21], v[32:33], v[22:23]
	v_cvt_pk_bf16_f32 v18, v18, v19
	v_cvt_pk_bf16_f32 v19, v20, v21
	global_store_dwordx2 v[74:75], v[18:19], off offset:288
	v_lshlrev_b32_e32 v18, 16, v80
	v_and_b32_e32 v19, 0xffff0000, v80
	v_pk_fma_f32 v[14:15], v[14:15], v[40:41], v[18:19]
	v_lshlrev_b32_e32 v18, 16, v81
	v_and_b32_e32 v19, 0xffff0000, v81
	v_pk_fma_f32 v[16:17], v[16:17], v[36:37], v[18:19]
	v_cvt_pk_bf16_f32 v14, v14, v15
	v_cvt_pk_bf16_f32 v15, v16, v17
	global_store_dwordx2 v[70:71], v[14:15], off offset:256
	v_lshlrev_b32_e32 v14, 16, v76
	v_and_b32_e32 v15, 0xffff0000, v76
	v_pk_fma_f32 v[10:11], v[10:11], v[30:31], v[14:15]
	v_lshlrev_b32_e32 v14, 16, v77
	v_and_b32_e32 v15, 0xffff0000, v77
	v_pk_fma_f32 v[12:13], v[12:13], v[32:33], v[14:15]
	v_cvt_pk_bf16_f32 v10, v10, v11
	v_cvt_pk_bf16_f32 v11, v12, v13
	global_store_dwordx2 v[70:71], v[10:11], off offset:288
	v_lshlrev_b32_e32 v10, 16, v72
	v_and_b32_e32 v11, 0xffff0000, v72
	v_pk_fma_f32 v[6:7], v[6:7], v[40:41], v[10:11]
	v_lshlrev_b32_e32 v10, 16, v73
	v_and_b32_e32 v11, 0xffff0000, v73
	v_pk_fma_f32 v[8:9], v[8:9], v[36:37], v[10:11]
	v_cvt_pk_bf16_f32 v6, v6, v7
	v_cvt_pk_bf16_f32 v7, v8, v9
	global_store_dwordx2 v[66:67], v[6:7], off offset:256
	v_lshlrev_b32_e32 v6, 16, v68
	v_and_b32_e32 v7, 0xffff0000, v68
	v_pk_fma_f32 v[2:3], v[2:3], v[30:31], v[6:7]
	v_lshlrev_b32_e32 v6, 16, v69
	v_and_b32_e32 v7, 0xffff0000, v69
	v_pk_fma_f32 v[4:5], v[4:5], v[32:33], v[6:7]
	v_cvt_pk_bf16_f32 v2, v2, v3
	v_cvt_pk_bf16_f32 v3, v4, v5
	global_store_dwordx2 v[66:67], v[2:3], off offset:288
	s_cbranch_scc1 .LBB0_1811
